# MLA attention item prologue: first K/V tile's loads issued together with the Q loads (were after the Q rotary processing)
# speedup vs baseline: 1.0010x; 1.0010x over previous
.LBB0_917:
	s_and_b32 s9, s11, 3
	s_add_i32 s12, s16, 0x100
	s_and_b64 s[6:7], exec, s[6:7]
	s_mul_i32 s11, s10, 0x900
	s_cselect_b32 s6, 0, s12
	s_mul_hi_i32 s8, s10, 0x900
	s_add_u32 s6, s11, s6
	s_addc_u32 s7, s8, 0
	s_lshl_b64 s[6:7], s[6:7], 11
	s_add_u32 s6, s74, s6
	s_addc_u32 s7, s75, s7
	s_mul_i32 s8, s9, 0xc0
	s_add_u32 s6, s6, s8
	s_addc_u32 s7, s7, 0
	s_mul_i32 s14, s10, 0x480000
	s_mul_hi_i32 s15, s10, 0x480000
	s_add_u32 s12, s74, s14
	s_addc_u32 s13, s75, s15
	s_add_u32 s10, s12, s8
	s_addc_u32 s11, s13, 0
	s_lshl_b32 s9, s9, 7
	s_add_u32 s12, s12, s9
	s_addc_u32 s13, s13, 0
	s_andn2_b64 vcc, exec, s[0:1]
	s_mov_b64 s[0:1], -1
	s_cbranch_vccnz .LBB0_939
	s_waitcnt vmcnt(2)
	v_mov_b32_e32 v58, v211
	s_movk_i32 s0, 0xffe0
	v_ashrrev_i32_e32 v12, 1, v58
	v_bfi_b32 v2, s0, v12, v58
	v_ashrrev_i32_e32 v3, 31, v2
	v_bfe_u32 v140, v58, 5, 1
	v_lshlrev_b64 v[2:3], 11, v[2:3]
	v_lshl_add_u64 v[2:3], s[6:7], 0, v[2:3]
	v_lshlrev_b32_e32 v0, 4, v140
	v_lshl_add_u64 v[10:11], v[2:3], 0, v[0:1]
	global_load_dwordx4 v[2:5], v[10:11], off offset:160
	global_load_dwordx4 v[6:9], v[10:11], off offset:128
	v_and_b32_e32 v141, 31, v58
	v_and_b32_e32 v130, 0xffffffe0, v12
	v_or_b32_e32 v12, s16, v141
	v_add_u32_e32 v12, v12, v130
	v_and_b32_e32 v13, 63, v12
	v_ashrrev_i32_e32 v12, 6, v12
	v_cvt_f32_i32_e32 v12, v12
	v_and_b32_e32 v59, 63, v58
	v_cvt_f32_ubyte0_e32 v13, v13
	v_cmp_gt_u32_e64 s[0:1], 32, v59
	global_load_dwordx4 v[78:81], v[10:11], off
	global_load_dwordx4 v[74:77], v[10:11], off offset:32
	global_load_dwordx4 v[70:73], v[10:11], off offset:64
	global_load_dwordx4 v[66:69], v[10:11], off offset:96
	v_ashrrev_i32_e32 v248, 3, v58
	v_ashrrev_i32_e32 v249, 31, v248
	v_lshlrev_b64 v[248:249], 11, v[248:249]
	v_lshl_add_u64 v[248:249], s[12:13], 0, v[248:249]
	v_lshlrev_b32_e32 v250, 3, v58
	v_and_b32_e32 v250, 56, v250
	v_lshlrev_b32_e32 v250, 1, v250
	v_mov_b32_e32 v251, 0
	v_lshl_add_u64 v[248:249], v[248:249], 0, v[250:251]
	global_load_dwordx4 v[236:239], v[248:249], off offset:1536
	v_ashrrev_i32_e32 v248, 4, v58
	v_ashrrev_i32_e32 v249, 31, v248
	v_lshlrev_b64 v[248:249], 11, v[248:249]
	v_lshl_add_u64 v[248:249], s[10:11], 0, v[248:249]
	v_lshlrev_b32_e32 v250, 4, v58
	v_and_b32_e32 v250, 0xf0, v250
	v_lshl_add_u64 v[248:249], v[248:249], 0, v[250:251]
	global_load_dwordx4 v[240:243], v[248:249], off offset:768
	v_mov_b32_e32 v250, 0x10000
	v_lshl_add_u64 v[248:249], v[248:249], 0, v[250:251]
	global_load_dwordx4 v[244:247], v[248:249], off offset:768
	v_cndmask_b32_e64 v38, v13, v12, s[0:1]
	v_mul_f32_e32 v13, 0x3dcccccd, v38
	v_mul_f32_e32 v14, 0x3d0186e3, v38
	v_mul_f32_e32 v12, 0x3ea1e89b, v38
	v_mul_f32_e32 v15, 0x3c23d70b, v38
	v_mul_f32_e32 v16, 0x3b4f3e39, v38
	v_mul_f32_e32 v17, 0.15915494, v13
	s_waitcnt vmcnt(10)
	v_mul_f32_e32 v18, 0.15915494, v14
	v_mul_f32_e32 v10, 0.15915494, v38
	v_mul_f32_e32 v12, 0.15915494, v12
	v_mul_f32_e32 v20, 0.15915494, v15
	s_waitcnt vmcnt(9)
	v_mul_f32_e32 v22, 0.15915494, v16
	v_sin_f32_e32 v15, v17
	v_cos_f32_e32 v14, v17
	v_sin_f32_e32 v17, v18
	v_cos_f32_e32 v16, v18
	v_sin_f32_e32 v11, v10
	v_cos_f32_e32 v10, v10
	v_sin_f32_e32 v13, v12
	v_cos_f32_e32 v12, v12
	v_sin_f32_e32 v19, v20
	v_cos_f32_e32 v18, v20
	v_mov_b32_e32 v28, v17
	v_mov_b32_e32 v29, v16
	v_sin_f32_e32 v21, v22
	v_cos_f32_e32 v20, v22
	v_mov_b32_e32 v22, v11
	v_mov_b32_e32 v23, v10
	v_mov_b32_e32 v24, v13
	v_mov_b32_e32 v25, v12
	v_mov_b32_e32 v26, v15
	v_mov_b32_e32 v27, v14
	v_mov_b32_e32 v30, v19
	v_mov_b32_e32 v31, v18
	v_lshlrev_b32_e32 v60, 4, v58
	v_readlane_b32 s36, v252, 0
	s_cmp_lg_u32 0, -1
	v_readlane_b32 s37, v252, 1
	s_cselect_b32 s16, 0, 0
	s_mov_b32 s5, s37
	v_readlane_b32 s38, v252, 2
	v_readlane_b32 s39, v252, 3
	v_readlane_b32 s40, v252, 4
	v_readlane_b32 s41, v252, 5
	v_readlane_b32 s42, v252, 6
	v_readlane_b32 s43, v252, 7
	v_readlane_b32 s44, v252, 8
	v_readlane_b32 s45, v252, 9
	v_readlane_b32 s46, v252, 10
	v_readlane_b32 s47, v252, 11
	v_readlane_b32 s48, v252, 12
	v_readlane_b32 s49, v252, 13
	v_readlane_b32 s50, v252, 14
	v_readlane_b32 s51, v252, 15
	s_mov_b32 s36, s37
	s_mov_b32 s38, s37
	s_mov_b32 s39, s37
	s_mov_b32 s40, s37
	s_mov_b32 s41, s37
	s_mov_b32 s42, s37
	s_mov_b32 s43, s37
	s_mov_b32 s44, s37
	s_mov_b32 s45, s37
	s_mov_b32 s46, s37
	s_mov_b32 s47, s37
	s_mov_b32 s48, s37
	s_mov_b32 s49, s37
	s_waitcnt vmcnt(8)
	v_lshlrev_b32_e32 v33, 16, v2
	v_and_b32_e32 v35, 0xffff0000, v2
	v_lshlrev_b32_e32 v37, 16, v3
	v_and_b32_e32 v3, 0xffff0000, v3
	s_waitcnt vmcnt(7)
	v_and_b32_e32 v2, 0xffff0000, v7
	v_lshlrev_b32_e32 v32, 16, v6
	v_and_b32_e32 v34, 0xffff0000, v6
	v_lshlrev_b32_e32 v36, 16, v7
	v_pk_mul_f32 v[16:17], v[16:17], v[2:3]
	v_pk_mul_f32 v[2:3], v[28:29], v[2:3]
	v_lshlrev_b32_e32 v7, 16, v4
	v_lshlrev_b32_e32 v6, 16, v8
	v_pk_mul_f32 v[10:11], v[10:11], v[32:33]
	v_pk_mul_f32 v[22:23], v[22:23], v[32:33]
	v_pk_mul_f32 v[12:13], v[12:13], v[34:35]
	v_pk_mul_f32 v[24:25], v[24:25], v[34:35]
	v_pk_mul_f32 v[14:15], v[14:15], v[36:37]
	v_pk_mul_f32 v[26:27], v[26:27], v[36:37]
	v_add_f32_e32 v2, v2, v3
	v_sub_f32_e32 v10, v10, v11
	v_add_f32_e32 v11, v22, v23
	v_sub_f32_e32 v12, v12, v13
	v_add_f32_e32 v13, v24, v25
	v_sub_f32_e32 v14, v14, v15
	v_add_f32_e32 v15, v26, v27
	v_sub_f32_e32 v16, v16, v17
	v_cvt_pk_bf16_f32 v86, v10, v12
	v_cvt_pk_bf16_f32 v82, v11, v13
	v_cvt_pk_bf16_f32 v87, v14, v16
	v_cvt_pk_bf16_f32 v83, v15, v2
	v_pk_mul_f32 v[2:3], v[30:31], v[6:7]
	v_pk_mul_f32 v[18:19], v[18:19], v[6:7]
	v_add_f32_e32 v10, v2, v3
	v_and_b32_e32 v3, 0xffff0000, v4
	v_and_b32_e32 v2, 0xffff0000, v8
	v_pk_mul_f32 v[6:7], v[20:21], v[2:3]
	v_sub_f32_e32 v17, v18, v19
	v_sub_f32_e32 v4, v6, v7
	v_mov_b32_e32 v6, v21
	v_mov_b32_e32 v7, v20
	v_pk_mul_f32 v[2:3], v[6:7], v[2:3]
	v_cvt_pk_bf16_f32 v88, v17, v4
	v_mul_f32_e32 v4, 0x39a5cb61, v38
	v_add_f32_e32 v2, v2, v3
	v_cvt_pk_bf16_f32 v84, v10, v2
	v_mul_f32_e32 v2, 0x3a831270, v38
	v_mul_f32_e32 v2, 0.15915494, v2
	v_sin_f32_e32 v3, v2
	v_cos_f32_e32 v2, v2
	v_mul_f32_e32 v4, 0.15915494, v4
	v_lshlrev_b32_e32 v11, 16, v5
	v_lshlrev_b32_e32 v10, 16, v9
	v_sin_f32_e32 v7, v4
	v_cos_f32_e32 v6, v4
	v_pk_mul_f32 v[12:13], v[2:3], v[10:11]
	v_ashrrev_i32_e32 v16, 3, v58
	v_sub_f32_e32 v8, v12, v13
	v_mov_b32_e32 v12, v3
	v_mov_b32_e32 v13, v2
	v_pk_mul_f32 v[2:3], v[12:13], v[10:11]
	v_ashrrev_i32_e32 v14, 4, v58
	v_add_f32_e32 v10, v2, v3
	v_and_b32_e32 v3, 0xffff0000, v5
	v_and_b32_e32 v2, 0xffff0000, v9
	v_pk_mul_f32 v[4:5], v[6:7], v[2:3]
	v_lshlrev_b32_e32 v22, 3, v58
	v_sub_f32_e32 v4, v4, v5
	v_cvt_pk_bf16_f32 v89, v8, v4
	v_mov_b32_e32 v4, v7
	v_mov_b32_e32 v5, v6
	v_pk_mul_f32 v[2:3], v[4:5], v[2:3]
	v_ashrrev_i32_e32 v17, 31, v16
	v_add_f32_e32 v2, v2, v3
	v_and_b32_e32 v4, 56, v22
	v_lshlrev_b64 v[50:51], 11, v[16:17]
	v_ashrrev_i32_e32 v15, 31, v14
	v_cvt_pk_bf16_f32 v85, v10, v2
	v_lshl_add_u64 v[2:3], s[12:13], 0, v[50:51]
	v_lshlrev_b32_e32 v4, 1, v4
	v_mov_b32_e32 v5, v1
	v_lshlrev_b64 v[52:53], 11, v[14:15]
	v_add_u32_e32 v20, 32, v14
	v_lshl_add_u64 v[54:55], v[2:3], 0, v[4:5]
	v_lshl_add_u64 v[2:3], s[10:11], 0, v[52:53]
	v_and_b32_e32 v18, 0xf0, v60
	v_mov_b32_e32 v19, v1
	v_ashrrev_i32_e32 v21, 31, v20
	v_lshl_add_u64 v[56:57], v[2:3], 0, v[18:19]
	v_and_b32_e32 v17, 0x1fffff0, v16
	v_lshlrev_b32_e32 v19, 1, v16
	v_lshrrev_b32_e32 v21, 1, v16
	v_and_b32_e32 v16, 3, v16
	v_and_or_b32 v17, v19, 8, v17
	v_bfe_u32 v22, v22, 5, 1
	v_and_b32_e32 v23, 48, v60
	v_and_or_b32 v16, v21, 4, v16
	v_lshrrev_b32_e32 v17, 2, v17
	v_lshl_or_b32 v16, v16, 6, v23
	v_or_b32_e32 v17, v17, v22
	v_lshl_or_b32 v16, v17, 9, v16
	v_and_b32_e32 v15, 0x70, v58
	v_lshlrev_b32_e32 v14, 8, v14
	v_add_u32_e32 v146, 0, v16
	s_waitcnt vmcnt(0)
	s_mov_b32 s50, s37
	s_mov_b32 s51, s37
	s_mov_b32 s24, 1
	v_mov_b32_e32 v144, 0
	s_waitcnt vmcnt(2)
	ds_write_b128 v146, v[236:239]
	v_bitop3_b32 v2, v18, v14, v15 bitop3:0xde
	v_add_u32_e32 v147, 0, v2
	v_lshlrev_b32_e32 v2, 8, v20
	v_bitop3_b32 v2, v18, v2, v15 bitop3:0xde
	v_add_u32_e32 v148, 0, v2
	s_waitcnt vmcnt(1)
	ds_write_b128 v147, v[240:243] offset:16384
	s_waitcnt vmcnt(0)
	ds_write_b128 v148, v[244:247] offset:16384
	v_lshlrev_b32_e32 v10, 8, v141
	v_and_b32_e32 v11, 0x70, v60
	v_bitop3_b32 v2, v0, v10, v11 bitop3:0xde
	v_add_u32_e32 v149, 0, v2
	s_waitcnt lgkmcnt(0)
	s_barrier
	ds_read_b128 v[2:5], v149 offset:16384
	ds_read_b128 v[6:9], v149 offset:24576
	s_waitcnt lgkmcnt(1)
	v_mfma_f32_32x32x16_bf16 v[34:49], v[2:5], v[78:81], 0
	v_or_b32_e32 v2, 32, v0
	v_bitop3_b32 v2, v2, v10, v11 bitop3:0xde
	v_add_u32_e32 v152, 0, v2
	v_and_b32_e32 v12, 0x3fffffc0, v58
	v_lshl_add_u32 v131, v12, 2, 0
	v_lshlrev_b32_e32 v12, 3, v59
	v_lshlrev_b32_e32 v14, 1, v58
	s_waitcnt lgkmcnt(0)
	v_mfma_f32_32x32x16_bf16 v[18:33], v[6:9], v[78:81], 0
	ds_read_b128 v[2:5], v152 offset:16384
	ds_read_b128 v[6:9], v152 offset:24576
	v_lshl_add_u32 v142, v141, 2, v131
	s_waitcnt lgkmcnt(1)
	v_mfma_f32_32x32x16_bf16 v[34:49], v[2:5], v[74:77], v[34:49]
	v_or_b32_e32 v2, 64, v0
	v_bitop3_b32 v2, v2, v10, v11 bitop3:0xde
	v_add_u32_e32 v151, 0, v2
	s_waitcnt lgkmcnt(0)
	v_mfma_f32_32x32x16_bf16 v[18:33], v[6:9], v[74:77], v[18:33]
	ds_read_b128 v[2:5], v151 offset:16384
	ds_read_b128 v[6:9], v151 offset:24576
	s_waitcnt lgkmcnt(1)
	v_mfma_f32_32x32x16_bf16 v[34:49], v[2:5], v[70:73], v[34:49]
	v_or_b32_e32 v2, 0x60, v0
	v_bitop3_b32 v2, v2, v10, v11 bitop3:0xde
	v_add_u32_e32 v150, 0, v2
	ds_read_b128 v[2:5], v150 offset:16384
	s_waitcnt lgkmcnt(1)
	v_mfma_f32_32x32x16_bf16 v[18:33], v[6:9], v[70:73], v[18:33]
	v_and_b32_e32 v6, 0xc0, v60
	v_and_or_b32 v13, v12, 24, v6
	ds_read_b128 v[6:9], v150 offset:24576
	s_waitcnt lgkmcnt(1)
	v_mfma_f32_32x32x16_bf16 v[34:49], v[2:5], v[66:69], v[34:49]
	v_or_b32_e32 v2, 0x80, v0
	v_bitop3_b32 v15, v2, v10, v11 bitop3:0xde
	v_add_co_u32_e32 v2, vcc, s52, v54
	v_add_u32_e32 v153, 0, v15
	s_nop 0
	v_addc_co_u32_e32 v3, vcc, 0, v55, vcc
	v_add_co_u32_e32 v4, vcc, s52, v56
	s_waitcnt lgkmcnt(0)
	v_mfma_f32_32x32x16_bf16 v[18:33], v[6:9], v[66:69], v[18:33]
	v_addc_co_u32_e32 v5, vcc, 0, v57, vcc
	global_load_dwordx4 v[60:63], v[2:3], off offset:1536
	global_load_dwordx4 v[102:105], v[4:5], off offset:768
	v_add_co_u32_e32 v2, vcc, s86, v56
	v_and_b32_e32 v6, 32, v14
	s_nop 0
	v_addc_co_u32_e32 v3, vcc, 0, v57, vcc
	global_load_dwordx4 v[106:109], v[2:3], off offset:768
	ds_read_b128 v[2:5], v153 offset:16384
	v_and_b32_e32 v7, 0x100, v12
	v_or3_b32 v59, v13, v6, v7
	ds_read_b128 v[6:9], v153 offset:24576
	s_waitcnt lgkmcnt(1)
	v_mfma_f32_32x32x16_bf16 v[34:49], v[2:5], v[86:89], v[34:49]
	v_or_b32_e32 v2, 0xa0, v0
	v_bitop3_b32 v2, v2, v10, v11 bitop3:0xde
	v_add_u32_e32 v154, 0, v2
	ds_read_b128 v[2:5], v154 offset:16384
	ds_read_b128 v[90:93], v154 offset:24576
	v_add_u32_e32 v145, s16, v59
	v_writelane_b32 v252, s4, 0
	s_waitcnt lgkmcnt(1)
	v_mfma_f32_32x32x16_bf16 v[34:49], v[2:5], v[82:85], v[34:49]
	v_writelane_b32 v252, s5, 1
	v_writelane_b32 v252, s6, 2
	v_writelane_b32 v252, s7, 3
	v_writelane_b32 v252, s8, 4
	v_writelane_b32 v252, s9, 5
	v_writelane_b32 v252, s10, 6
	v_writelane_b32 v252, s11, 7
	v_mfma_f32_32x32x16_bf16 v[18:33], v[6:9], v[86:89], v[18:33]
	s_nop 3
	v_max_f32_e32 v64, v35, v35
	v_max_f32_e32 v65, v34, v34
	v_max_f32_e32 v64, v65, v64
	v_max3_f32 v64, v64, v36, v37
	v_max3_f32 v64, v64, v38, v39
	v_max3_f32 v64, v64, v40, v41
	v_max3_f32 v64, v64, v42, v43
	s_waitcnt lgkmcnt(0)
	v_mfma_f32_32x32x16_bf16 v[18:33], v[90:93], v[82:85], v[18:33]
	v_max3_f32 v64, v64, v44, v45
	v_max3_f32 v64, v64, v46, v47
	v_writelane_b32 v252, s12, 8
	v_max3_f32 v64, v64, v48, v49
	v_writelane_b32 v252, s13, 9
	v_writelane_b32 v252, s14, 10
	v_writelane_b32 v252, s15, 11
	s_nop 4
	v_max3_f32 v64, v64, v18, v19
	v_max3_f32 v64, v64, v20, v21
	v_max3_f32 v64, v64, v22, v23
	v_writelane_b32 v252, s16, 12
	v_max3_f32 v64, v64, v24, v25
	v_writelane_b32 v252, s17, 13
	v_max3_f32 v64, v64, v26, v27
	v_writelane_b32 v252, s18, 14
	v_max3_f32 v64, v64, v28, v29
	v_writelane_b32 v252, s19, 15
	v_max3_f32 v64, v64, v30, v31
	s_mov_b32 s4, 0x50000
	v_max3_f32 v110, v64, v32, v33
	v_add_co_u32_e32 v64, vcc, s4, v56
	s_mov_b32 s4, 0x40000
	s_nop 0
	v_addc_co_u32_e32 v65, vcc, 0, v57, vcc
	v_add_co_u32_e32 v56, vcc, s4, v56
	global_load_dwordx4 v[94:97], v[64:65], off offset:768
	s_nop 0
	v_addc_co_u32_e32 v57, vcc, 0, v57, vcc
	v_add_co_u32_e32 v54, vcc, s4, v54
	v_mov_b64_e32 v[2:3], s[36:37]
	s_nop 0
	v_addc_co_u32_e32 v55, vcc, 0, v55, vcc
	global_load_dwordx4 v[98:101], v[56:57], off offset:768
	global_load_dwordx4 v[90:93], v[54:55], off offset:1536
	v_mov_b32_e32 v54, v110
	s_nop 1
	v_permlane32_swap_b32_e32 v110, v54
	v_max_f32_e32 v54, v54, v54
	v_max_f32_e32 v55, v110, v110
	v_max_f32_e32 v54, v55, v54
	v_add_f32_e32 v55, 0x7149f2ca, v54
	v_cmp_ge_f32_e32 vcc, s72, v55
	s_cmp_eq_u64 vcc, exec
	v_max_f32_e32 v55, 0xf149f2ca, v54
	s_cselect_b64 vcc, -1, 0
	v_mov_b32_e32 v54, 0xf149f2ca
	v_cndmask_b32_e32 v118, v55, v54, vcc
	v_mul_f32_e32 v54, 0xbe16c740, v118
	v_fmamk_f32 v34, v34, 0x3e16c740, v54
	v_exp_f32_e32 v128, v34
	v_fmamk_f32 v34, v35, 0x3e16c740, v54
	v_exp_f32_e32 v138, v34
	v_fmamk_f32 v34, v36, 0x3e16c740, v54
	v_exp_f32_e32 v129, v34
	v_fmamk_f32 v34, v37, 0x3e16c740, v54
	v_exp_f32_e32 v139, v34
	v_fmamk_f32 v34, v38, 0x3e16c740, v54
	v_exp_f32_e32 v136, v34
	v_fmamk_f32 v34, v39, 0x3e16c740, v54
	v_exp_f32_e32 v159, v34
	v_fmamk_f32 v34, v40, 0x3e16c740, v54
	v_exp_f32_e32 v137, v34
	v_fmamk_f32 v34, v41, 0x3e16c740, v54
	v_exp_f32_e32 v160, v34
	v_fmamk_f32 v34, v42, 0x3e16c740, v54
	v_exp_f32_e32 v120, v34
	v_fmamk_f32 v34, v43, 0x3e16c740, v54
	v_exp_f32_e32 v123, v34
	v_fmamk_f32 v34, v44, 0x3e16c740, v54
	v_exp_f32_e32 v121, v34
	v_fmamk_f32 v34, v45, 0x3e16c740, v54
	v_exp_f32_e32 v124, v34
	v_fmamk_f32 v34, v46, 0x3e16c740, v54
	v_exp_f32_e32 v122, v34
	v_fmamk_f32 v34, v47, 0x3e16c740, v54
	v_sub_f32_e32 v35, 0xf149f2ca, v55
	v_pk_fma_f32 v[116:117], v[18:19], s[96:97], v[54:55] op_sel_hi:[1,0,0]
	v_and_b32_e32 v18, 15, v58
	v_mov_b64_e32 v[4:5], s[38:39]
	v_mov_b64_e32 v[6:7], s[40:41]
	v_mov_b64_e32 v[8:9], s[42:43]
	v_mov_b64_e32 v[10:11], s[44:45]
	v_mov_b64_e32 v[12:13], s[46:47]
	v_mov_b64_e32 v[14:15], s[48:49]
	v_mov_b64_e32 v[16:17], s[50:51]
	v_exp_f32_e32 v125, v34
	v_fmamk_f32 v34, v48, 0x3e16c740, v54
	v_mul_f32_e32 v35, 0x3e16c740, v35
	v_or_b32_e32 v52, s8, v52
	v_lshlrev_b32_e32 v18, 4, v18
	v_mov_b32_e32 v19, v1
	v_readlane_b32 s36, v252, 18
	v_exp_f32_e32 v35, v35
	v_exp_f32_e32 v126, v34
	v_fmamk_f32 v34, v49, 0x3e16c740, v54
	v_lshl_add_u64 v[18:19], v[52:53], 0, v[18:19]
	v_readlane_b32 s40, v252, 22
	v_readlane_b32 s41, v252, 23
	v_exp_f32_e32 v127, v34
	s_waitcnt vmcnt(3)
	s_waitcnt vmcnt(5)
	ds_write_b128 v146, v[60:63] offset:8192
	s_waitcnt vmcnt(4)
	ds_write_b128 v147, v[102:105] offset:32768
	s_waitcnt vmcnt(3)
	ds_write_b128 v148, v[106:109] offset:32768
	v_lshl_add_u64 v[132:133], s[40:41], 0, v[18:19]
	v_and_b32_e32 v18, 7, v58
	v_lshlrev_b32_e32 v18, 4, v18
	v_pk_fma_f32 v[102:103], v[32:33], s[96:97], v[54:55] op_sel_hi:[1,0,0]
	v_pk_fma_f32 v[108:109], v[30:31], s[96:97], v[54:55] op_sel_hi:[1,0,0]
	v_pk_fma_f32 v[112:113], v[28:29], s[96:97], v[54:55] op_sel_hi:[1,0,0]
	v_pk_fma_f32 v[104:105], v[26:27], s[96:97], v[54:55] op_sel_hi:[1,0,0]
	v_pk_fma_f32 v[106:107], v[24:25], s[96:97], v[54:55] op_sel_hi:[1,0,0]
	v_pk_fma_f32 v[110:111], v[22:23], s[96:97], v[54:55] op_sel_hi:[1,0,0]
	v_pk_fma_f32 v[114:115], v[20:21], s[96:97], v[54:55] op_sel_hi:[1,0,0]
	s_addk_i32 s16, 0x2000
	v_or3_b32 v50, v50, s9, v18
	v_mov_b64_e32 v[32:33], v[16:17]
	v_cndmask_b32_e64 v155, v35, 1.0, vcc
	v_add_u32_e32 v143, s16, v59
	v_lshl_add_u64 v[134:135], s[40:41], 0, v[50:51]
	v_mov_b64_e32 v[30:31], v[14:15]
	v_mov_b64_e32 v[28:29], v[12:13]
	v_mov_b64_e32 v[26:27], v[10:11]
	v_mov_b64_e32 v[24:25], v[8:9]
	v_mov_b64_e32 v[22:23], v[6:7]
	v_mov_b64_e32 v[20:21], v[4:5]
	v_mov_b64_e32 v[18:19], v[2:3]
	s_mov_b32 s4, 0x15cf1000
	s_waitcnt lgkmcnt(0)
	s_barrier
	v_readlane_b32 s37, v252, 19
	v_readlane_b32 s38, v252, 20
	v_readlane_b32 s39, v252, 21
	v_readlane_b32 s42, v252, 24
	v_readlane_b32 s43, v252, 25
